# attention steady loops: K/V LDS-DMA addresses via SGPR base + 32-bit VGPR offset (no v_lshl_add_u64), m0 save/restore removed; on top of ticket/lambda prefetches
# speedup vs baseline: 1.0058x; 1.0058x over previous
.LBB0_394:
	s_and_b64 s[2:3], s[0:1], exec
	s_cselect_b32 s58, s14, s15
	s_or_b32 s96, s58, s52
	s_ashr_i32 s97, s96, 31
	s_lshl_b64 s[2:3], s[96:97], 10
	v_mov_b32_e32 v34, v215
	s_add_u32 s59, s53, s2
	s_addc_u32 s68, s54, s3
	v_readfirstlane_b32 s34, v34
	s_ashr_i32 s69, s34, 6
	s_lshl_b32 s4, s69, 5
	s_ashr_i32 s5, s4, 31
	s_lshl_b64 s[2:3], s[4:5], 10
	v_and_b32_e32 v224, 63, v34
	s_add_u32 s38, s59, s2
	s_addc_u32 s39, s68, s3
	v_lshlrev_b32_e32 v204, 10, v224
	s_lshl_b32 s2, s69, 3
	v_lshl_add_u64 v[0:1], s[88:89], 0, v[204:205]
	s_ashr_i32 s3, s2, 31
	v_lshl_add_u64 v[206:207], s[2:3], 1, v[0:1]
	s_lshl_b32 s2, s69, 4
	v_bfe_u32 v194, v34, 2, 4
	v_and_or_b32 v0, s2, 48, v194
	s_ashr_i32 s2, s34, 3
	v_lshlrev_b32_e32 v204, 10, v0
	s_and_b32 s10, s2, 0xffffffe0
	v_lshlrev_b32_e32 v2, 3, v34
	v_lshl_add_u64 v[0:1], s[90:91], 0, v[204:205]
	s_ashr_i32 s11, s10, 31
	v_and_b32_e32 v227, 24, v2
	v_lshl_add_u64 v[0:1], s[10:11], 1, v[0:1]
	v_lshlrev_b32_e32 v204, 1, v227
	s_lshl_b32 s2, s69, 10
	v_lshl_add_u64 v[32:33], v[0:1], 0, v[204:205]
	s_cmp_lg_u32 0, -1
	v_lshlrev_b32_e32 v0, 1, v34
	s_cselect_b32 s3, 0, 0
	v_and_b32_e32 v228, 32, v0
	v_lshlrev_b32_e32 v0, 4, v34
	v_bfe_u32 v222, v34, 5, 1
	s_add_i32 s2, s2, s3
	v_and_b32_e32 v0, 0xc0, v0
	s_mov_b32 s3, m0
	s_mov_b32 m0, s2
	s_nop 0
	global_load_lds_dwordx4 v[206:207], off
	s_mov_b32 m0, s3
	s_add_i32 s35, s2, 0x6000
	v_lshl_or_b32 v226, v222, 8, v0
	s_mov_b32 s3, m0
	s_mov_b32 m0, s35
	s_nop 0
	global_load_lds_dwordx4 v[32:33], off
	s_mov_b32 m0, s3
	v_lshl_add_u64 v[0:1], v[32:33], 0, s[8:9]
	v_and_b32_e32 v221, 31, v34
	s_add_i32 s3, s2, 0x8000
	s_mov_b32 s37, m0
	s_mov_b32 m0, s3
	s_nop 0
	global_load_lds_dwordx4 v[0:1], off
	s_mov_b32 m0, s37
	v_lshl_add_u64 v[0:1], v[206:207], 0, s[12:13]
	s_add_i32 s37, s2, 0x2000
	s_mov_b32 s40, m0
	s_mov_b32 m0, s37
	s_nop 0
	global_load_lds_dwordx4 v[0:1], off
	s_mov_b32 m0, s40
	v_lshlrev_b32_e32 v0, 10, v221
	v_lshl_or_b32 v0, v222, 4, v0
	global_load_dwordx4 v[128:131], v0, s[38:39]
	global_load_dwordx4 v[132:135], v0, s[38:39] offset:32
	global_load_dwordx4 v[136:139], v0, s[38:39] offset:64
	global_load_dwordx4 v[140:143], v0, s[38:39] offset:96
	v_lshlrev_b32_e32 v225, 10, v222
	v_lshlrev_b32_e32 v2, 4, v221
	v_lshl_add_u64 v[0:1], v[206:207], 0, s[16:17]
	s_add_i32 s37, s2, 0x4000
	s_mov_b32 s38, m0
	s_mov_b32 m0, s37
	s_nop 0
	global_load_lds_dwordx4 v[0:1], off
	s_mov_b32 m0, s38
	v_add_u32_e32 v3, 0, v228
	v_add3_u32 v229, 0, v225, v2
	s_waitcnt vmcnt(3) lgkmcnt(0)
	s_barrier
	v_add3_u32 v230, v3, v227, v226
	ds_read_b128 v[16:19], v229 offset:512
	ds_read_b128 v[0:3], v229
	ds_read_b128 v[36:39], v229 offset:2560
	ds_read_b128 v[40:43], v229 offset:2048
	s_add_i32 s5, s58, 0x100
	s_lshr_b32 s57, s5, 6
	s_mov_b32 s6, 1
	s_mov_b32 s36, 0
	s_movk_i32 s3, 0x2000
	s_movk_i32 s66, 0x4000
	s_waitcnt vmcnt(3) lgkmcnt(2)
	v_mfma_f32_32x32x16_bf16 v[0:15], v[0:3], v[128:131], 0
	v_mfma_f32_32x32x16_bf16 v[16:31], v[16:19], v[128:131], 0
	s_waitcnt vmcnt(2) lgkmcnt(0)
	v_mfma_f32_32x32x16_bf16 v[0:15], v[40:43], v[132:135], v[0:15]
	v_mfma_f32_32x32x16_bf16 v[16:31], v[36:39], v[132:135], v[16:31]
	ds_read_b128 v[36:39], v229 offset:4608
	ds_read_b128 v[40:43], v229 offset:4096
	s_waitcnt vmcnt(1) lgkmcnt(0)
	v_mfma_f32_32x32x16_bf16 v[0:15], v[40:43], v[136:139], v[0:15]
	v_mfma_f32_32x32x16_bf16 v[16:31], v[36:39], v[136:139], v[16:31]
	ds_read_b128 v[36:39], v229 offset:6656
	ds_read_b128 v[40:43], v229 offset:6144
	s_waitcnt vmcnt(0) lgkmcnt(0)
	v_mfma_f32_32x32x16_bf16 v[0:15], v[40:43], v[140:143], v[0:15]
	v_mfma_f32_32x32x16_bf16 v[16:31], v[36:39], v[140:143], v[16:31]
	s_nop 15
	s_nop 7
	s_waitcnt vmcnt(0) lgkmcnt(0)
	s_barrier
	s_nop 10
	v_exp_f32_e32 v64, v0
	v_exp_f32_e32 v65, v1
	v_lshl_add_u64 v[0:1], v[206:207], 0, s[18:19]
	s_mov_b32 s5, m0
	s_mov_b32 m0, s2
	s_nop 0
	global_load_lds_dwordx4 v[0:1], off
	s_mov_b32 m0, s5
	v_lshl_add_u64 v[0:1], v[32:33], 0, s[12:13]
	s_add_i32 s5, s2, 0xa000
	s_mov_b32 s64, m0
	s_mov_b32 m0, s5
	s_nop 0
	global_load_lds_dwordx4 v[0:1], off
	s_mov_b32 m0, s64
	v_lshl_add_u64 v[0:1], v[32:33], 0, s[70:71]
	s_add_i32 s5, s2, 0xc000
	s_mov_b32 s64, m0
	s_mov_b32 m0, s5
	s_nop 0
	global_load_lds_dwordx4 v[0:1], off
	s_mov_b32 m0, s64
	ds_read_b128 v[188:191], v229 offset:8192
	ds_read_b128 v[180:183], v229 offset:8704
	ds_read_b128 v[184:187], v229 offset:10240
	ds_read_b128 v[176:179], v229 offset:10752
	ds_read_b128 v[172:175], v229 offset:12288
	ds_read_b128 v[168:171], v229 offset:12800
	ds_read_b128 v[164:167], v229 offset:14336
	ds_read_b128 v[160:163], v229 offset:14848
	v_exp_f32_e32 v66, v2
	v_exp_f32_e32 v67, v3
	v_exp_f32_e32 v68, v4
	v_exp_f32_e32 v69, v5
	v_exp_f32_e32 v70, v6
	v_exp_f32_e32 v71, v7
	s_waitcnt vmcnt(3) lgkmcnt(0)
	s_barrier
	s_cmp_lg_u32 s58, 0
	v_and_b32_e32 v0, 3, v34
	s_cselect_b64 s[64:65], -1, 0
	s_cmp_eq_u32 s58, 0
	v_lshlrev_b32_e32 v204, 4, v0
	s_cbranch_scc1 .LBB0_441
	s_lshl_b32 s3, s34, 8
	s_and_b32 s3, s3, 0xc000
	v_lshl_add_u64 v[0:1], s[10:11], 1, v[204:205]
	v_lshl_or_b32 v2, v194, 10, s3
	v_mov_b32_e32 v3, v205
	v_lshl_add_u64 v[0:1], v[0:1], 0, v[2:3]
	v_mov_b32_e32 v231, 0
	v_lshl_add_u64 v[192:193], s[92:93], 0, v[0:1]
	s_movk_i32 s3, 0x2000
	s_mov_b32 s37, 0
	s_mov_b32 s40, 6
	s_mov_b64 s[38:39], 0
	v_mov_b32_e32 v0, 0
	v_mov_b32_e32 v1, v231
	v_mov_b32_e32 v2, v231
	v_mov_b32_e32 v3, v231
	v_mov_b32_e32 v4, v231
	v_mov_b32_e32 v5, v231
	v_mov_b32_e32 v6, v231
	v_mov_b32_e32 v7, v231
	v_mov_b32_e32 v8, v231
	v_mov_b32_e32 v9, v231
	v_mov_b32_e32 v10, v231
	v_mov_b32_e32 v11, v231
	v_mov_b32_e32 v12, v231
	v_mov_b32_e32 v13, v231
	v_mov_b32_e32 v14, v231
	v_mov_b32_e32 v15, v231
	v_mov_b32_e32 v16, 0
	v_mov_b32_e32 v17, v231
	v_mov_b32_e32 v18, v231
	v_mov_b32_e32 v19, v231
	v_mov_b32_e32 v20, v231
	v_mov_b32_e32 v21, v231
	v_mov_b32_e32 v22, v231
	v_mov_b32_e32 v23, v231
	v_mov_b32_e32 v24, v231
	v_mov_b32_e32 v25, v231
	v_mov_b32_e32 v26, v231
	v_mov_b32_e32 v27, v231
	v_mov_b32_e32 v28, v231
	v_mov_b32_e32 v29, v231
	v_mov_b32_e32 v30, v231
	v_mov_b32_e32 v31, v231
	v_mov_b32_e32 v32, 0
	v_mov_b32_e32 v33, v231
	v_mov_b32_e32 v34, v231
	v_mov_b32_e32 v35, v231
	v_mov_b32_e32 v36, v231
	v_mov_b32_e32 v37, v231
	v_mov_b32_e32 v38, v231
	v_mov_b32_e32 v39, v231
	v_mov_b32_e32 v40, v231
	v_mov_b32_e32 v41, v231
	v_mov_b32_e32 v42, v231
	v_mov_b32_e32 v43, v231
	v_mov_b32_e32 v44, v231
	v_mov_b32_e32 v45, v231
	v_mov_b32_e32 v46, v231
	v_mov_b32_e32 v47, v231
	v_mov_b32_e32 v48, 0
	v_mov_b32_e32 v49, v231
	v_mov_b32_e32 v50, v231
	v_mov_b32_e32 v51, v231
	v_mov_b32_e32 v52, v231
	v_mov_b32_e32 v53, v231
	v_mov_b32_e32 v54, v231
	v_mov_b32_e32 v55, v231
	v_mov_b32_e32 v56, v231
	v_mov_b32_e32 v57, v231
	v_mov_b32_e32 v58, v231
	v_mov_b32_e32 v59, v231
	v_mov_b32_e32 v60, v231
	v_mov_b32_e32 v61, v231
	v_mov_b32_e32 v62, v231
	v_mov_b32_e32 v63, v231
	v_mov_b32_e32 v80, 0
	v_mov_b32_e32 v81, v231
	v_mov_b32_e32 v82, v231
	v_mov_b32_e32 v83, v231
	v_mov_b32_e32 v84, v231
	v_mov_b32_e32 v85, v231
	v_mov_b32_e32 v86, v231
	v_mov_b32_e32 v87, v231
	v_mov_b32_e32 v88, v231
	v_mov_b32_e32 v89, v231
	v_mov_b32_e32 v90, v231
	v_mov_b32_e32 v91, v231
	v_mov_b32_e32 v92, v231
	v_mov_b32_e32 v93, v231
	v_mov_b32_e32 v94, v231
	v_mov_b32_e32 v95, v231
	v_mov_b32_e32 v72, v231
	v_mov_b32_e32 v73, v231
	v_mov_b32_e32 v74, v231
	v_mov_b32_e32 v75, v231
	v_mov_b32_e32 v76, v231
	v_mov_b32_e32 v77, v231
	v_mov_b32_e32 v78, v231
	v_mov_b32_e32 v79, v231
	v_readfirstlane_b32 s98, v192
	v_readfirstlane_b32 s99, v193
	s_nop 1
	v_subrev_u32_e32 v238, s98, v206
	v_subrev_u32_e32 v239, s98, v192
	s_add_u32 s98, s98, s38
	s_addc_u32 s99, s99, s39
.LBB0_396:
	s_mov_b32 s36, s66
	s_mov_b32 s5, s40
	s_mov_b32 s6, s3
	v_lshl_add_u32 v195, s37, 1, v230
	ds_read_b64_tr_b16 v[196:197], v195 offset:24576
	ds_read_b64_tr_b16 v[198:199], v195 offset:25088
	v_add_f32_e32 v96, v64, v65
	v_add_f32_e32 v96, v66, v96
	v_add_f32_e32 v96, v67, v96
	v_add_f32_e32 v96, v68, v96
	v_add_f32_e32 v96, v69, v96
	v_cvt_pk_bf16_f32 v144, v64, v65
	v_cvt_pk_bf16_f32 v145, v66, v67
	s_waitcnt lgkmcnt(9)
	v_mfma_f32_32x32x16_bf16 v[112:127], v[188:191], v[128:131], 0
	ds_read_b64_tr_b16 v[64:65], v195 offset:28672
	ds_read_b64_tr_b16 v[66:67], v195 offset:29184
	v_add_f32_e32 v96, v70, v96
	v_add_f32_e32 v96, v71, v96
	v_add_f32_e32 v96, v72, v96
	v_add_f32_e32 v148, v73, v96
	v_cvt_pk_bf16_f32 v146, v68, v69
	v_cvt_pk_bf16_f32 v147, v70, v71
	s_waitcnt lgkmcnt(10)
	v_mfma_f32_32x32x16_bf16 v[96:111], v[180:183], v[128:131], 0
	ds_read_b64_tr_b16 v[68:69], v195 offset:25600
	ds_read_b64_tr_b16 v[70:71], v195 offset:26112
	v_add_f32_e32 v148, v74, v148
	v_add_f32_e32 v148, v75, v148
	v_add_f32_e32 v148, v76, v148
	v_add_f32_e32 v152, v77, v148
	v_cvt_pk_bf16_f32 v148, v72, v73
	v_cvt_pk_bf16_f32 v149, v74, v75
	s_waitcnt lgkmcnt(11)
	v_mfma_f32_32x32x16_bf16 v[112:127], v[184:187], v[132:135], v[112:127]
	ds_read_b64_tr_b16 v[72:73], v195 offset:29696
	ds_read_b64_tr_b16 v[74:75], v195 offset:30208
	v_add_f32_e32 v150, v78, v152
	v_add_f32_e32 v150, v79, v150
	v_add_f32_e32 v150, v80, v150
	v_add_f32_e32 v152, v81, v150
	v_cvt_pk_bf16_f32 v150, v76, v77
	v_cvt_pk_bf16_f32 v151, v78, v79
	s_waitcnt lgkmcnt(12)
	v_mfma_f32_32x32x16_bf16 v[96:111], v[176:179], v[132:135], v[96:111]
	ds_read_b64_tr_b16 v[76:77], v195 offset:26624
	ds_read_b64_tr_b16 v[78:79], v195 offset:27136
	v_add_f32_e32 v152, v82, v152
	v_add_f32_e32 v152, v83, v152
	v_add_f32_e32 v152, v84, v152
	v_add_f32_e32 v156, v85, v152
	v_cvt_pk_bf16_f32 v152, v80, v81
	v_cvt_pk_bf16_f32 v153, v82, v83
	s_waitcnt lgkmcnt(13)
	v_mfma_f32_32x32x16_bf16 v[112:127], v[172:175], v[136:139], v[112:127]
	ds_read_b64_tr_b16 v[200:201], v195 offset:30720
	ds_read_b64_tr_b16 v[202:203], v195 offset:31232
	v_add_f32_e32 v80, v86, v156
	v_add_f32_e32 v80, v87, v80
	v_add_f32_e32 v80, v88, v80
	v_add_f32_e32 v80, v89, v80
	v_cvt_pk_bf16_f32 v154, v84, v85
	v_cvt_pk_bf16_f32 v155, v86, v87
	s_waitcnt lgkmcnt(14)
	v_mfma_f32_32x32x16_bf16 v[96:111], v[168:171], v[136:139], v[96:111]
	ds_read_b64_tr_b16 v[84:85], v195 offset:27648
	ds_read_b64_tr_b16 v[86:87], v195 offset:28160
	v_add_f32_e32 v80, v90, v80
	v_add_f32_e32 v80, v91, v80
	v_add_f32_e32 v80, v92, v80
	v_add_f32_e32 v80, v93, v80
	v_cvt_pk_bf16_f32 v156, v88, v89
	v_cvt_pk_bf16_f32 v157, v90, v91
	s_waitcnt lgkmcnt(14)
	v_mfma_f32_32x32x16_bf16 v[112:127], v[164:167], v[140:143], v[112:127]
	ds_read_b64_tr_b16 v[88:89], v195 offset:31744
	ds_read_b64_tr_b16 v[90:91], v195 offset:32256
	v_add_f32_e32 v80, v94, v80
	v_add_f32_e32 v80, v95, v80
	v_add_f32_e32 v80, 0, v80
	v_cvt_pk_bf16_f32 v158, v92, v93
	v_cvt_pk_bf16_f32 v159, v94, v95
	v_mfma_f32_32x32x16_bf16 v[96:111], v[160:163], v[140:143], v[96:111]
	s_add_i32 s3, s3, s2
	v_add_f32_e32 v188, v231, v80
	s_mov_b32 m0, s3
	s_add_u32 s100, s98, s72
	s_addc_u32 s101, s99, s73
	global_load_lds_dwordx4 v238, s[100:101]
	s_lshl_b32 s3, s66, 1
	s_add_i32 s3, s3, s35
	s_mov_b32 m0, s3
	s_add_u32 s100, s98, s74
	s_addc_u32 s101, s99, s75
	global_load_lds_dwordx4 v239, s[100:101]
	s_addk_i32 s3, 0x2000
	s_mov_b32 m0, s3
	s_add_u32 s100, s98, s76
	s_addc_u32 s101, s99, s77
	global_load_lds_dwordx4 v239, s[100:101]
	s_waitcnt lgkmcnt(14)
	v_mfma_f32_32x32x16_bf16 v[0:15], v[144:147], v[196:199], v[0:15]
	v_exp_f32_e32 v112, v112
	v_exp_f32_e32 v113, v113
	ds_read_b64_tr_b16 v[92:93], v195 offset:32768
	ds_read_b64_tr_b16 v[94:95], v195 offset:33280
	s_waitcnt lgkmcnt(14)
	v_mfma_f32_32x32x16_bf16 v[16:31], v[144:147], v[64:67], v[16:31]
	v_exp_f32_e32 v114, v114
	v_exp_f32_e32 v115, v115
	ds_read_b64_tr_b16 v[196:197], v195 offset:36864
	ds_read_b64_tr_b16 v[198:199], v195 offset:37376
	v_add_u32_e32 v160, s36, v229
	ds_read_b128 v[64:67], v160
	ds_read_b128 v[80:83], v160 offset:512
	s_waitcnt lgkmcnt(14)
	v_mfma_f32_32x32x16_bf16 v[0:15], v[148:151], v[68:71], v[0:15]
	v_exp_f32_e32 v116, v116
	v_exp_f32_e32 v117, v117
	ds_read_b64_tr_b16 v[68:69], v195 offset:33792
	ds_read_b64_tr_b16 v[70:71], v195 offset:34304
	ds_read_b128 v[180:183], v160 offset:2048
	ds_read_b128 v[176:179], v160 offset:2560
	v_mfma_f32_32x32x16_bf16 v[16:31], v[148:151], v[72:75], v[16:31]
	v_exp_f32_e32 v118, v118
	v_exp_f32_e32 v119, v119
	ds_read_b64_tr_b16 v[72:73], v195 offset:37888
	ds_read_b64_tr_b16 v[74:75], v195 offset:38400
	ds_read_b128 v[172:175], v160 offset:4096
	ds_read_b128 v[168:171], v160 offset:4608
	s_waitcnt lgkmcnt(14)
	v_mfma_f32_32x32x16_bf16 v[0:15], v[152:155], v[76:79], v[0:15]
	v_exp_f32_e32 v120, v120
	v_exp_f32_e32 v121, v121
	ds_read_b64_tr_b16 v[76:77], v195 offset:34816
	ds_read_b64_tr_b16 v[78:79], v195 offset:35328
	ds_read_b128 v[164:167], v160 offset:6144
	ds_read_b128 v[160:163], v160 offset:6656
	v_mfma_f32_32x32x16_bf16 v[16:31], v[152:155], v[200:203], v[16:31]
	v_exp_f32_e32 v122, v122
	v_exp_f32_e32 v123, v123
	ds_read_b64_tr_b16 v[200:201], v195 offset:38912
	ds_read_b64_tr_b16 v[202:203], v195 offset:39424
	v_mfma_f32_32x32x16_bf16 v[0:15], v[156:159], v[84:87], v[0:15]
	v_exp_f32_e32 v124, v124
	v_exp_f32_e32 v125, v125
	ds_read_b64_tr_b16 v[84:85], v195 offset:35840
	ds_read_b64_tr_b16 v[86:87], v195 offset:36352
	v_mfma_f32_32x32x16_bf16 v[16:31], v[156:159], v[88:91], v[16:31]
	v_exp_f32_e32 v126, v126
	v_exp_f32_e32 v127, v127
	ds_read_b64_tr_b16 v[88:89], v195 offset:39936
	ds_read_b64_tr_b16 v[90:91], v195 offset:40448
	s_waitcnt lgkmcnt(14)
	v_mfma_f32_32x32x16_bf16 v[32:47], v[144:147], v[92:95], v[32:47]
	v_exp_f32_e32 v96, v96
	v_exp_f32_e32 v97, v97
	v_mfma_f32_32x32x16_bf16 v[48:63], v[144:147], v[196:199], v[48:63]
	v_exp_f32_e32 v98, v98
	v_exp_f32_e32 v99, v99
	v_mfma_f32_32x32x16_bf16 v[32:47], v[148:151], v[68:71], v[32:47]
	v_exp_f32_e32 v100, v100
	v_exp_f32_e32 v101, v101
	s_waitcnt lgkmcnt(12)
	v_mfma_f32_32x32x16_bf16 v[48:63], v[148:151], v[72:75], v[48:63]
	v_exp_f32_e32 v102, v102
	v_exp_f32_e32 v103, v103
	s_waitcnt lgkmcnt(8)
	v_mfma_f32_32x32x16_bf16 v[32:47], v[152:155], v[76:79], v[32:47]
	v_exp_f32_e32 v104, v104
	v_exp_f32_e32 v105, v105
	s_waitcnt lgkmcnt(4)
	v_mfma_f32_32x32x16_bf16 v[48:63], v[152:155], v[200:203], v[48:63]
	v_exp_f32_e32 v106, v106
	v_exp_f32_e32 v107, v107
	s_waitcnt lgkmcnt(2)
	v_mfma_f32_32x32x16_bf16 v[32:47], v[156:159], v[84:87], v[32:47]
	v_exp_f32_e32 v108, v108
	v_exp_f32_e32 v109, v109
	s_waitcnt lgkmcnt(0)
	v_mfma_f32_32x32x16_bf16 v[48:63], v[156:159], v[88:91], v[48:63]
	v_exp_f32_e32 v110, v110
	v_exp_f32_e32 v111, v111
	s_waitcnt vmcnt(3) lgkmcnt(0)
	s_barrier
	s_add_i32 s3, s66, 0x2000
	s_cmpk_lg_i32 s66, 0x4000
	s_cselect_b32 s3, s3, 0
	v_lshl_add_u32 v195, s6, 1, v230
	ds_read_b64_tr_b16 v[196:197], v195 offset:24576
	ds_read_b64_tr_b16 v[198:199], v195 offset:25088
	v_add_f32_e32 v68, v112, v113
	v_add_f32_e32 v68, v114, v68
	v_add_f32_e32 v68, v115, v68
	v_add_f32_e32 v68, v116, v68
	v_add_f32_e32 v84, v117, v68
	v_mfma_f32_32x32x16_bf16 v[64:79], v[64:67], v[128:131], 0
	v_cvt_pk_bf16_f32 v144, v112, v113
	v_cvt_pk_bf16_f32 v145, v114, v115
	ds_read_b64_tr_b16 v[112:113], v195 offset:28672
	ds_read_b64_tr_b16 v[114:115], v195 offset:29184
	v_add_f32_e32 v84, v118, v84
	v_add_f32_e32 v84, v119, v84
	v_add_f32_e32 v84, v120, v84
	v_add_f32_e32 v148, v121, v84
	v_mfma_f32_32x32x16_bf16 v[80:95], v[80:83], v[128:131], 0
	v_cvt_pk_bf16_f32 v146, v116, v117
	v_cvt_pk_bf16_f32 v147, v118, v119
	ds_read_b64_tr_b16 v[116:117], v195 offset:25600
	ds_read_b64_tr_b16 v[118:119], v195 offset:26112
	v_mfma_f32_32x32x16_bf16 v[64:79], v[180:183], v[132:135], v[64:79]
	v_add_f32_e32 v148, v122, v148
	v_add_f32_e32 v148, v123, v148
	v_add_f32_e32 v148, v124, v148
	v_add_f32_e32 v152, v125, v148
	v_cvt_pk_bf16_f32 v148, v120, v121
	v_cvt_pk_bf16_f32 v149, v122, v123
	ds_read_b64_tr_b16 v[120:121], v195 offset:29696
	ds_read_b64_tr_b16 v[122:123], v195 offset:30208
	v_mfma_f32_32x32x16_bf16 v[80:95], v[176:179], v[132:135], v[80:95]
	v_add_f32_e32 v150, v126, v152
	v_add_f32_e32 v150, v127, v150
	v_add_f32_e32 v150, v96, v150
	v_add_f32_e32 v152, v97, v150
	v_cvt_pk_bf16_f32 v150, v124, v125
	v_cvt_pk_bf16_f32 v151, v126, v127
	ds_read_b64_tr_b16 v[124:125], v195 offset:26624
	ds_read_b64_tr_b16 v[126:127], v195 offset:27136
	v_mfma_f32_32x32x16_bf16 v[64:79], v[172:175], v[136:139], v[64:79]
	v_add_f32_e32 v152, v98, v152
	v_add_f32_e32 v152, v99, v152
	v_add_f32_e32 v152, v100, v152
	v_add_f32_e32 v156, v101, v152
	v_cvt_pk_bf16_f32 v152, v96, v97
	v_cvt_pk_bf16_f32 v153, v98, v99
	ds_read_b64_tr_b16 v[96:97], v195 offset:30720
	ds_read_b64_tr_b16 v[98:99], v195 offset:31232
	v_mfma_f32_32x32x16_bf16 v[80:95], v[168:171], v[136:139], v[80:95]
	v_add_f32_e32 v154, v102, v156
	v_add_f32_e32 v154, v103, v154
	v_add_f32_e32 v154, v104, v154
	v_add_f32_e32 v156, v105, v154
	v_cvt_pk_bf16_f32 v154, v100, v101
	v_cvt_pk_bf16_f32 v155, v102, v103
	ds_read_b64_tr_b16 v[100:101], v195 offset:27648
	ds_read_b64_tr_b16 v[102:103], v195 offset:28160
	v_mfma_f32_32x32x16_bf16 v[64:79], v[164:167], v[140:143], v[64:79]
	v_add_f32_e32 v156, v106, v156
	v_add_f32_e32 v156, v107, v156
	v_add_f32_e32 v156, v108, v156
	v_add_f32_e32 v164, v109, v156
	v_cvt_pk_bf16_f32 v156, v104, v105
	v_cvt_pk_bf16_f32 v157, v106, v107
	ds_read_b64_tr_b16 v[104:105], v195 offset:31744
	ds_read_b64_tr_b16 v[106:107], v195 offset:32256
	v_mfma_f32_32x32x16_bf16 v[80:95], v[160:163], v[140:143], v[80:95]
	v_add_f32_e32 v158, v110, v164
	v_add_f32_e32 v158, v111, v158
	v_add_f32_e32 v160, 0, v158
	v_cvt_pk_bf16_f32 v158, v108, v109
	v_cvt_pk_bf16_f32 v159, v110, v111
	s_add_i32 s6, s66, s2
	s_mov_b32 m0, s6
	s_add_u32 s100, s98, s78
	s_addc_u32 s101, s99, s79
	global_load_lds_dwordx4 v238, s[100:101]
	s_lshl_b32 s6, s3, 1
	s_add_i32 s6, s6, s35
	s_mov_b32 m0, s6
	s_add_u32 s100, s98, s80
	s_addc_u32 s101, s99, s81
	global_load_lds_dwordx4 v239, s[100:101]
	s_addk_i32 s6, 0x2000
	s_mov_b32 m0, s6
	s_add_u32 s100, s98, s82
	s_addc_u32 s101, s99, s83
	global_load_lds_dwordx4 v239, s[100:101]
	v_add_f32_e32 v231, v188, v160
	s_waitcnt lgkmcnt(14)
	v_mfma_f32_32x32x16_bf16 v[0:15], v[144:147], v[196:199], v[0:15]
	v_exp_f32_e32 v64, v64
	v_exp_f32_e32 v65, v65
	ds_read_b64_tr_b16 v[108:109], v195 offset:32768
	ds_read_b64_tr_b16 v[110:111], v195 offset:33280
	s_waitcnt lgkmcnt(14)
	v_mfma_f32_32x32x16_bf16 v[16:31], v[144:147], v[112:115], v[16:31]
	v_exp_f32_e32 v66, v66
	v_exp_f32_e32 v67, v67
	ds_read_b64_tr_b16 v[112:113], v195 offset:36864
	ds_read_b64_tr_b16 v[114:115], v195 offset:37376
	v_add_u32_e32 v160, s3, v229
	ds_read_b128 v[188:191], v160
	ds_read_b128 v[180:183], v160 offset:512
	s_waitcnt lgkmcnt(14)
	v_mfma_f32_32x32x16_bf16 v[0:15], v[148:151], v[116:119], v[0:15]
	v_exp_f32_e32 v68, v68
	v_exp_f32_e32 v69, v69
	ds_read_b64_tr_b16 v[116:117], v195 offset:33792
	ds_read_b64_tr_b16 v[118:119], v195 offset:34304
	ds_read_b128 v[184:187], v160 offset:2048
	ds_read_b128 v[176:179], v160 offset:2560
	v_mfma_f32_32x32x16_bf16 v[16:31], v[148:151], v[120:123], v[16:31]
	v_exp_f32_e32 v70, v70
	v_exp_f32_e32 v71, v71
	ds_read_b64_tr_b16 v[120:121], v195 offset:37888
	ds_read_b64_tr_b16 v[122:123], v195 offset:38400
	ds_read_b128 v[172:175], v160 offset:4096
	ds_read_b128 v[168:171], v160 offset:4608
	s_waitcnt lgkmcnt(14)
	v_mfma_f32_32x32x16_bf16 v[0:15], v[152:155], v[124:127], v[0:15]
	v_exp_f32_e32 v72, v72
	v_exp_f32_e32 v73, v73
	ds_read_b64_tr_b16 v[124:125], v195 offset:34816
	ds_read_b64_tr_b16 v[126:127], v195 offset:35328
	ds_read_b128 v[164:167], v160 offset:6144
	ds_read_b128 v[160:163], v160 offset:6656
	v_mfma_f32_32x32x16_bf16 v[16:31], v[152:155], v[96:99], v[16:31]
	v_exp_f32_e32 v74, v74
	v_exp_f32_e32 v75, v75
	ds_read_b64_tr_b16 v[96:97], v195 offset:38912
	ds_read_b64_tr_b16 v[98:99], v195 offset:39424
	v_mfma_f32_32x32x16_bf16 v[0:15], v[156:159], v[100:103], v[0:15]
	v_exp_f32_e32 v76, v76
	v_exp_f32_e32 v77, v77
	ds_read_b64_tr_b16 v[100:101], v195 offset:35840
	ds_read_b64_tr_b16 v[102:103], v195 offset:36352
	v_mfma_f32_32x32x16_bf16 v[16:31], v[156:159], v[104:107], v[16:31]
	v_exp_f32_e32 v78, v78
	v_exp_f32_e32 v79, v79
	ds_read_b64_tr_b16 v[104:105], v195 offset:39936
	ds_read_b64_tr_b16 v[106:107], v195 offset:40448
	s_waitcnt lgkmcnt(14)
	v_mfma_f32_32x32x16_bf16 v[32:47], v[144:147], v[108:111], v[32:47]
	v_exp_f32_e32 v80, v80
	v_exp_f32_e32 v81, v81
	v_mfma_f32_32x32x16_bf16 v[48:63], v[144:147], v[112:115], v[48:63]
	v_exp_f32_e32 v82, v82
	v_exp_f32_e32 v83, v83
	v_mfma_f32_32x32x16_bf16 v[32:47], v[148:151], v[116:119], v[32:47]
	v_exp_f32_e32 v84, v84
	v_exp_f32_e32 v85, v85
	s_waitcnt lgkmcnt(12)
	v_mfma_f32_32x32x16_bf16 v[48:63], v[148:151], v[120:123], v[48:63]
	v_exp_f32_e32 v86, v86
	v_exp_f32_e32 v87, v87
	s_waitcnt lgkmcnt(8)
	v_mfma_f32_32x32x16_bf16 v[32:47], v[152:155], v[124:127], v[32:47]
	v_exp_f32_e32 v88, v88
	v_exp_f32_e32 v89, v89
	s_waitcnt lgkmcnt(4)
	v_mfma_f32_32x32x16_bf16 v[48:63], v[152:155], v[96:99], v[48:63]
	v_exp_f32_e32 v90, v90
	v_exp_f32_e32 v91, v91
	s_waitcnt lgkmcnt(2)
	v_mfma_f32_32x32x16_bf16 v[32:47], v[156:159], v[100:103], v[32:47]
	v_exp_f32_e32 v92, v92
	v_exp_f32_e32 v93, v93
	s_waitcnt lgkmcnt(0)
	v_mfma_f32_32x32x16_bf16 v[48:63], v[156:159], v[104:107], v[48:63]
	v_exp_f32_e32 v94, v94
	v_exp_f32_e32 v95, v95
	s_add_i32 s6, s3, 0x2000
	s_cmpk_lg_i32 s3, 0x4000
	s_cselect_b32 s66, s6, 0
	s_add_i32 s40, s40, 2
	s_waitcnt vmcnt(3) lgkmcnt(0)
	s_barrier
	s_add_u32 s38, s38, 0x20000
	s_addc_u32 s39, s39, 0
	s_add_u32 s98, s98, 0x20000
	s_addc_u32 s99, s99, 0
	s_cmp_gt_u32 s40, s57
	s_mov_b32 s37, s36
	s_cbranch_scc0 .LBB0_396
	s_add_i32 s6, s5, -3
	s_xor_b64 s[94:95], s[0:1], -1
	s_cmp_lt_u32 s6, s57
	s_mov_b64 s[0:1], -1
	s_cbranch_scc1 .LBB0_399

.LBB0_435:
	v_add_f32_e32 v96, v64, v65
	v_add_f32_e32 v96, v66, v96
	v_add_f32_e32 v96, v67, v96
	v_add_f32_e32 v96, v68, v96
	v_add_f32_e32 v96, v69, v96
	v_add_f32_e32 v96, v70, v96
	v_add_f32_e32 v96, v71, v96
	v_add_f32_e32 v96, v72, v96
	v_add_f32_e32 v96, v73, v96
	v_add_f32_e32 v96, v74, v96
	v_add_f32_e32 v96, v75, v96
	v_add_f32_e32 v96, v76, v96
	v_add_f32_e32 v96, v77, v96
	v_add_f32_e32 v96, v78, v96
	v_add_f32_e32 v96, v79, v96
	v_add_f32_e32 v96, v80, v96
	v_add_f32_e32 v96, v81, v96
	v_add_f32_e32 v96, v82, v96
	v_add_f32_e32 v96, v83, v96
	v_add_f32_e32 v96, v84, v96
	v_add_f32_e32 v96, v85, v96
	v_add_f32_e32 v96, v86, v96
	v_add_f32_e32 v96, v87, v96
	v_add_f32_e32 v96, v88, v96
	v_add_f32_e32 v96, v89, v96
	v_add_f32_e32 v96, v90, v96
	v_add_f32_e32 v96, v91, v96
	s_and_b32 s0, s34, 0x3fffffc0
	v_add_f32_e32 v96, v92, v96
	s_cmp_lg_u32 0, -1
	v_add_f32_e32 v96, v93, v96
	s_cselect_b32 s1, 0, 0
	s_lshl_b32 s0, s0, 2
	v_add_f32_e32 v96, v94, v96
	s_add_i32 s2, s0, 0
	v_add_f32_e32 v96, v95, v96
	s_addk_i32 s1, 0x6000
	s_add_i32 s2, s2, 0x12000
	v_add_f32_e32 v96, v231, v96
	v_cvt_pk_bf16_f32 v64, v64, v65
	v_add3_u32 v97, v228, s1, v227
	v_cvt_pk_bf16_f32 v65, v66, v67
	v_cvt_pk_bf16_f32 v66, v68, v69
	v_cvt_pk_bf16_f32 v67, v70, v71
	v_cvt_pk_bf16_f32 v68, v72, v73
	v_cvt_pk_bf16_f32 v69, v74, v75
	v_cvt_pk_bf16_f32 v70, v76, v77
	v_cvt_pk_bf16_f32 v71, v78, v79
	v_cvt_pk_bf16_f32 v72, v80, v81
	v_cvt_pk_bf16_f32 v73, v82, v83
	v_cvt_pk_bf16_f32 v74, v84, v85
	v_cvt_pk_bf16_f32 v75, v86, v87
	v_cvt_pk_bf16_f32 v76, v88, v89
	v_cvt_pk_bf16_f32 v77, v90, v91
	v_cvt_pk_bf16_f32 v78, v92, v93
	v_cvt_pk_bf16_f32 v79, v94, v95
	v_add3_u32 v97, v97, v226, s41
	ds_read_b64_tr_b16 v[80:81],v97 offset:0
	ds_read_b64_tr_b16 v[82:83],v97 offset:512
	ds_read_b64_tr_b16 v[84:85],v97 offset:1024
	ds_read_b64_tr_b16 v[86:87],v97 offset:1536
	ds_read_b64_tr_b16 v[88:89],v97 offset:2048
	ds_read_b64_tr_b16 v[90:91],v97 offset:2560
	ds_read_b64_tr_b16 v[92:93],v97 offset:3072
	ds_read_b64_tr_b16 v[94:95],v97 offset:3584
	s_waitcnt lgkmcnt(0)
	s_nop 0
	v_mfma_f32_32x32x16_bf16 v[0:15], v[64:67], v[80:83], v[0:15]
	ds_read_b64_tr_b16 v[80:81],v97 offset:4096
	ds_read_b64_tr_b16 v[82:83],v97 offset:4608
	v_mfma_f32_32x32x16_bf16 v[0:15], v[68:71], v[84:87], v[0:15]
	ds_read_b64_tr_b16 v[84:85],v97 offset:5120
	ds_read_b64_tr_b16 v[86:87],v97 offset:5632
	v_mfma_f32_32x32x16_bf16 v[0:15], v[72:75], v[88:91], v[0:15]
	ds_read_b64_tr_b16 v[88:89],v97 offset:6144
	ds_read_b64_tr_b16 v[90:91],v97 offset:6656
	v_mfma_f32_32x32x16_bf16 v[0:15], v[76:79], v[92:95], v[0:15]
	ds_read_b64_tr_b16 v[92:93],v97 offset:7168
	ds_read_b64_tr_b16 v[94:95],v97 offset:7680
	s_waitcnt lgkmcnt(0)
	v_mfma_f32_32x32x16_bf16 v[16:31], v[64:67], v[80:83], v[16:31]
	ds_read_b64_tr_b16 v[80:81],v97 offset:8192
	ds_read_b64_tr_b16 v[82:83],v97 offset:8704
	v_mfma_f32_32x32x16_bf16 v[16:31], v[68:71], v[84:87], v[16:31]
	ds_read_b64_tr_b16 v[84:85],v97 offset:9216
	ds_read_b64_tr_b16 v[86:87],v97 offset:9728
	v_mfma_f32_32x32x16_bf16 v[16:31], v[72:75], v[88:91], v[16:31]
	ds_read_b64_tr_b16 v[88:89],v97 offset:10240
	ds_read_b64_tr_b16 v[90:91],v97 offset:10752
	v_mfma_f32_32x32x16_bf16 v[16:31], v[76:79], v[92:95], v[16:31]
	ds_read_b64_tr_b16 v[92:93],v97 offset:11264
	ds_read_b64_tr_b16 v[94:95],v97 offset:11776
	s_waitcnt lgkmcnt(0)
	v_mfma_f32_32x32x16_bf16 v[32:47], v[64:67], v[80:83], v[32:47]
	ds_read_b64_tr_b16 v[80:81],v97 offset:12288
	ds_read_b64_tr_b16 v[82:83],v97 offset:12800
	v_mfma_f32_32x32x16_bf16 v[32:47], v[68:71], v[84:87], v[32:47]
	ds_read_b64_tr_b16 v[84:85],v97 offset:13312
	ds_read_b64_tr_b16 v[86:87],v97 offset:13824
	v_mfma_f32_32x32x16_bf16 v[32:47], v[72:75], v[88:91], v[32:47]
	ds_read_b64_tr_b16 v[88:89],v97 offset:14336
	ds_read_b64_tr_b16 v[90:91],v97 offset:14848
	v_mfma_f32_32x32x16_bf16 v[32:47], v[76:79], v[92:95], v[32:47]
	ds_read_b64_tr_b16 v[92:93],v97 offset:15360
	ds_read_b64_tr_b16 v[94:95],v97 offset:15872
	s_waitcnt lgkmcnt(0)
	v_mfma_f32_32x32x16_bf16 v[48:63], v[64:67], v[80:83], v[48:63]
	v_mov_b32_e32 v64, v96
	s_nop 1
	v_permlane32_swap_b32_e32 v96, v64
	v_cmp_gt_u32_e32 vcc, 32, v224
	v_mfma_f32_32x32x16_bf16 v[48:63], v[68:71], v[84:87], v[48:63]
	v_mfma_f32_32x32x16_bf16 v[48:63], v[72:75], v[88:91], v[48:63]
	v_mfma_f32_32x32x16_bf16 v[48:63], v[76:79], v[92:95], v[48:63]
	s_and_saveexec_b64 s[0:1], vcc
	v_add_f32_e32 v64, v96, v64
	v_lshl_add_u32 v65, v221, 2, s2
	ds_write_b32 v65, v64 offset:128
	s_or_b64 exec, exec, s[0:1]
	s_waitcnt lgkmcnt(0)
	v_lshl_add_u32 v72, v222, 4, s2
	ds_read_b128 v[64:67], v72 offset:128
	ds_read_b128 v[68:71], v72 offset:160
	s_lshl_b32 s0, s69, 13
	s_add_i32 s0, s0, 0
	s_add_i32 s0, s0, 0x12800
	s_waitcnt lgkmcnt(1)
	v_rcp_f32_e32 v73, v64
	v_rcp_f32_e32 v74, v65
	v_rcp_f32_e32 v75, v66
	v_rcp_f32_e32 v76, v67
	s_waitcnt lgkmcnt(0)
	v_rcp_f32_e32 v77, v68
	ds_read_b128 v[64:67], v72 offset:192
	v_rcp_f32_e32 v78, v69
	v_rcp_f32_e32 v79, v70
	v_rcp_f32_e32 v80, v71
	ds_read_b128 v[68:71], v72 offset:224
	v_lshlrev_b32_e32 v72, 1, v221
	v_mul_f32_e32 v0, v0, v73
	v_add3_u32 v72, s0, v225, v72
	v_cvt_pk_bf16_f32 v0, v0, s0
	ds_write_b16 v72, v0
	v_mul_f32_e32 v0, v16, v73
	v_cvt_pk_bf16_f32 v0, v0, s0
	ds_write_b16 v72, v0 offset:64
	v_mul_f32_e32 v0, v32, v73
	v_cvt_pk_bf16_f32 v0, v0, s0
	ds_write_b16 v72, v0 offset:128
	v_mul_f32_e32 v0, v48, v73
	v_cvt_pk_bf16_f32 v0, v0, s0
	ds_write_b16 v72, v0 offset:192
	v_mul_f32_e32 v0, v1, v74
	v_cvt_pk_bf16_f32 v0, v0, s0
	ds_write_b16 v72, v0 offset:256
	v_mul_f32_e32 v0, v17, v74
	v_cvt_pk_bf16_f32 v0, v0, s0
	ds_write_b16 v72, v0 offset:320
	v_mul_f32_e32 v0, v33, v74
	v_cvt_pk_bf16_f32 v0, v0, s0
	ds_write_b16 v72, v0 offset:384
	v_mul_f32_e32 v0, v49, v74
	v_cvt_pk_bf16_f32 v0, v0, s0
	ds_write_b16 v72, v0 offset:448
	v_mul_f32_e32 v0, v2, v75
	v_cvt_pk_bf16_f32 v0, v0, s0
	ds_write_b16 v72, v0 offset:512
	v_mul_f32_e32 v0, v18, v75
	v_cvt_pk_bf16_f32 v0, v0, s0
	ds_write_b16 v72, v0 offset:576
	v_mul_f32_e32 v0, v34, v75
	v_cvt_pk_bf16_f32 v0, v0, s0
	ds_write_b16 v72, v0 offset:640
	v_mul_f32_e32 v0, v50, v75
	v_cvt_pk_bf16_f32 v0, v0, s0
	ds_write_b16 v72, v0 offset:704
	v_mul_f32_e32 v0, v3, v76
	v_cvt_pk_bf16_f32 v0, v0, s0
	ds_write_b16 v72, v0 offset:768
	v_mul_f32_e32 v0, v19, v76
	v_cvt_pk_bf16_f32 v0, v0, s0
	ds_write_b16 v72, v0 offset:832
	v_mul_f32_e32 v0, v35, v76
	v_cvt_pk_bf16_f32 v0, v0, s0
	ds_write_b16 v72, v0 offset:896
	v_mul_f32_e32 v0, v51, v76
	v_cvt_pk_bf16_f32 v0, v0, s0
	ds_write_b16 v72, v0 offset:960
	v_mul_f32_e32 v0, v4, v77
	v_cvt_pk_bf16_f32 v0, v0, s0
	ds_write_b16 v72, v0 offset:2048
	v_mul_f32_e32 v0, v20, v77
	v_cvt_pk_bf16_f32 v0, v0, s0
	ds_write_b16 v72, v0 offset:2112
	v_mul_f32_e32 v0, v36, v77
	v_cvt_pk_bf16_f32 v0, v0, s0
	ds_write_b16 v72, v0 offset:2176
	v_mul_f32_e32 v0, v52, v77
	v_cvt_pk_bf16_f32 v0, v0, s0
	ds_write_b16 v72, v0 offset:2240
	v_mul_f32_e32 v0, v5, v78
	v_cvt_pk_bf16_f32 v0, v0, s0
	ds_write_b16 v72, v0 offset:2304
	v_mul_f32_e32 v0, v21, v78
	v_cvt_pk_bf16_f32 v0, v0, s0
	ds_write_b16 v72, v0 offset:2368
	v_mul_f32_e32 v0, v37, v78
	v_cvt_pk_bf16_f32 v0, v0, s0
	ds_write_b16 v72, v0 offset:2432
	v_mul_f32_e32 v0, v53, v78
	v_cvt_pk_bf16_f32 v0, v0, s0
	ds_write_b16 v72, v0 offset:2496
	v_mul_f32_e32 v0, v6, v79
	v_cvt_pk_bf16_f32 v0, v0, s0
	ds_write_b16 v72, v0 offset:2560
	v_mul_f32_e32 v0, v22, v79
	v_cvt_pk_bf16_f32 v0, v0, s0
	ds_write_b16 v72, v0 offset:2624
	v_mul_f32_e32 v0, v38, v79
	v_cvt_pk_bf16_f32 v0, v0, s0
	ds_write_b16 v72, v0 offset:2688
	v_mul_f32_e32 v0, v54, v79
	v_cvt_pk_bf16_f32 v0, v0, s0
	ds_write_b16 v72, v0 offset:2752
	v_mul_f32_e32 v0, v7, v80
	v_cvt_pk_bf16_f32 v0, v0, s0
	ds_write_b16 v72, v0 offset:2816
	v_mul_f32_e32 v0, v23, v80
	v_cvt_pk_bf16_f32 v0, v0, s0
	s_waitcnt lgkmcnt(14)
	v_rcp_f32_e32 v64, v64
	ds_write_b16 v72, v0 offset:2880
	v_mul_f32_e32 v0, v39, v80
	v_cvt_pk_bf16_f32 v0, v0, s0
	ds_write_b16 v72, v0 offset:2944
	v_mul_f32_e32 v0, v55, v80
	v_cvt_pk_bf16_f32 v0, v0, s0
	ds_write_b16 v72, v0 offset:3008
	v_mul_f32_e32 v0, v8, v64
	v_cvt_pk_bf16_f32 v0, v0, s0
	ds_write_b16 v72, v0 offset:4096
	v_mul_f32_e32 v0, v24, v64
	v_cvt_pk_bf16_f32 v0, v0, s0
	v_rcp_f32_e32 v65, v65
	ds_write_b16 v72, v0 offset:4160
	v_mul_f32_e32 v0, v40, v64
	v_cvt_pk_bf16_f32 v0, v0, s0
	ds_write_b16 v72, v0 offset:4224
	v_mul_f32_e32 v0, v56, v64
	v_cvt_pk_bf16_f32 v0, v0, s0
	ds_write_b16 v72, v0 offset:4288
	v_mul_f32_e32 v0, v9, v65
	v_cvt_pk_bf16_f32 v0, v0, s0
	ds_write_b16 v72, v0 offset:4352
	v_mul_f32_e32 v0, v25, v65
	v_cvt_pk_bf16_f32 v0, v0, s0
	v_rcp_f32_e32 v66, v66
	ds_write_b16 v72, v0 offset:4416
	v_mul_f32_e32 v0, v41, v65
	v_cvt_pk_bf16_f32 v0, v0, s0
	ds_write_b16 v72, v0 offset:4480
	v_mul_f32_e32 v0, v57, v65
	v_cvt_pk_bf16_f32 v0, v0, s0
	ds_write_b16 v72, v0 offset:4544
	v_mul_f32_e32 v0, v10, v66
	v_cvt_pk_bf16_f32 v0, v0, s0
	ds_write_b16 v72, v0 offset:4608
	v_mul_f32_e32 v0, v26, v66
	v_cvt_pk_bf16_f32 v0, v0, s0
	v_rcp_f32_e32 v67, v67
	ds_write_b16 v72, v0 offset:4672
	v_mul_f32_e32 v0, v42, v66
	v_cvt_pk_bf16_f32 v0, v0, s0
	ds_write_b16 v72, v0 offset:4736
	v_mul_f32_e32 v0, v58, v66
	v_cvt_pk_bf16_f32 v0, v0, s0
	ds_write_b16 v72, v0 offset:4800
	v_mul_f32_e32 v0, v11, v67
	v_cvt_pk_bf16_f32 v0, v0, s0
	ds_write_b16 v72, v0 offset:4864
	v_mul_f32_e32 v0, v27, v67
	v_cvt_pk_bf16_f32 v0, v0, s0
	v_rcp_f32_e32 v68, v68
	ds_write_b16 v72, v0 offset:4928
	v_mul_f32_e32 v0, v43, v67
	v_cvt_pk_bf16_f32 v0, v0, s0
	ds_write_b16 v72, v0 offset:4992
	v_mul_f32_e32 v0, v59, v67
	v_cvt_pk_bf16_f32 v0, v0, s0
	ds_write_b16 v72, v0 offset:5056
	v_mul_f32_e32 v0, v12, v68
	v_cvt_pk_bf16_f32 v0, v0, s0
	ds_write_b16 v72, v0 offset:6144
	v_mul_f32_e32 v0, v28, v68
	v_cvt_pk_bf16_f32 v0, v0, s0
	v_rcp_f32_e32 v69, v69
	ds_write_b16 v72, v0 offset:6208
	v_mul_f32_e32 v0, v44, v68
	v_cvt_pk_bf16_f32 v0, v0, s0
	ds_write_b16 v72, v0 offset:6272
	v_mul_f32_e32 v0, v60, v68
	v_cvt_pk_bf16_f32 v0, v0, s0
	ds_write_b16 v72, v0 offset:6336
	v_mul_f32_e32 v0, v13, v69
	v_cvt_pk_bf16_f32 v0, v0, s0
	ds_write_b16 v72, v0 offset:6400
	v_mul_f32_e32 v0, v29, v69
	v_cvt_pk_bf16_f32 v0, v0, s0
	v_rcp_f32_e32 v70, v70
	ds_write_b16 v72, v0 offset:6464
	v_mul_f32_e32 v0, v45, v69
	v_cvt_pk_bf16_f32 v0, v0, s0
	ds_write_b16 v72, v0 offset:6528
	v_mul_f32_e32 v0, v61, v69
	v_cvt_pk_bf16_f32 v0, v0, s0
	ds_write_b16 v72, v0 offset:6592
	v_mul_f32_e32 v0, v14, v70
	v_cvt_pk_bf16_f32 v0, v0, s0
	ds_write_b16 v72, v0 offset:6656
	v_mul_f32_e32 v0, v30, v70
	v_cvt_pk_bf16_f32 v0, v0, s0
	v_rcp_f32_e32 v71, v71
	ds_write_b16 v72, v0 offset:6720
	v_mul_f32_e32 v0, v46, v70
	v_cvt_pk_bf16_f32 v0, v0, s0
	ds_write_b16 v72, v0 offset:6784
	v_mul_f32_e32 v0, v62, v70
	v_cvt_pk_bf16_f32 v0, v0, s0
	ds_write_b16 v72, v0 offset:6848
	v_mul_f32_e32 v0, v15, v71
	v_cvt_pk_bf16_f32 v0, v0, s0
	ds_write_b16 v72, v0 offset:6912
	v_mul_f32_e32 v0, v31, v71
	v_cvt_pk_bf16_f32 v0, v0, s0
	ds_write_b16 v72, v0 offset:6976
	v_mul_f32_e32 v0, v47, v71
	v_cvt_pk_bf16_f32 v0, v0, s0
	ds_write_b16 v72, v0 offset:7040
	v_mul_f32_e32 v0, v63, v71
	v_cvt_pk_bf16_f32 v0, v0, s0
	ds_write_b16 v72, v0 offset:7104
	s_waitcnt lgkmcnt(0)
	v_mov_b32_e32 v195, v215
	s_waitcnt lgkmcnt(0)
	s_barrier
	s_movk_i32 s66, 0x4000
	v_readfirstlane_b32 s2, v195
	s_ashr_i32 s34, s2, 6
	s_lshl_b32 s10, s34, 5
	s_ashr_i32 s11, s10, 31
	s_lshl_b64 s[0:1], s[10:11], 10
	v_and_b32_e32 v227, 63, v195
	s_add_u32 s4, s59, s0
	s_addc_u32 s5, s68, s1
	v_lshlrev_b32_e32 v204, 10, v227
	s_lshl_b32 s0, s34, 3
	v_lshl_add_u64 v[0:1], s[88:89], 0, v[204:205]
	s_ashr_i32 s1, s0, 31
	v_lshl_add_u64 v[44:45], s[0:1], 1, v[0:1]
	s_lshl_b32 s0, s34, 4
	v_bfe_u32 v194, v195, 2, 4
	v_and_or_b32 v0, s0, 48, v194
	s_ashr_i32 s0, s2, 3
	s_andn2_b32 s0, s0, 31
	v_lshlrev_b32_e32 v204, 10, v0
	s_ashr_i32 s1, s0, 31
	v_lshlrev_b32_e32 v2, 3, v195
	s_lshl_b32 s3, s34, 10
	v_lshl_add_u64 v[0:1], s[90:91], 0, v[204:205]
	v_and_b32_e32 v228, 24, v2
	s_cmp_lg_u32 0, -1
	v_lshl_add_u64 v[0:1], s[0:1], 1, v[0:1]
	v_lshlrev_b32_e32 v204, 1, v228
	s_cselect_b32 s6, 0, 0
	v_lshl_add_u64 v[206:207], v[44:45], 0, s[8:9]
	v_lshl_add_u64 v[46:47], v[0:1], 0, v[204:205]
	s_add_i32 s3, s3, s6
	s_mov_b32 s6, m0
	s_mov_b32 m0, s3
	s_nop 0
	global_load_lds_dwordx4 v[206:207], off
	s_mov_b32 m0, s6
	s_add_i32 s35, s3, 0x6000
	s_mov_b32 s6, m0
	s_mov_b32 m0, s35
	s_nop 0
	global_load_lds_dwordx4 v[46:47], off
	s_mov_b32 m0, s6
	v_lshl_add_u64 v[0:1], v[46:47], 0, s[8:9]
	v_and_b32_e32 v224, 31, v195
	s_add_i32 s6, s3, 0x8000
	s_mov_b32 s36, m0
	s_mov_b32 m0, s6
	s_nop 0
	global_load_lds_dwordx4 v[0:1], off
	s_mov_b32 m0, s36
	v_lshl_add_u64 v[0:1], v[44:45], 0, s[70:71]
	v_bfe_u32 v226, v195, 5, 1
	s_add_i32 s6, s3, 0x2000
	s_mov_b32 s36, m0
	s_mov_b32 m0, s6
	s_nop 0
	global_load_lds_dwordx4 v[0:1], off
	s_mov_b32 m0, s36
	v_lshlrev_b32_e32 v0, 10, v224
	v_lshl_or_b32 v0, v226, 4, v0
	global_load_dwordx4 v[128:131], v0, s[4:5] offset:128
	global_load_dwordx4 v[132:135], v0, s[4:5] offset:160
	global_load_dwordx4 v[136:139], v0, s[4:5] offset:192
	global_load_dwordx4 v[140:143], v0, s[4:5] offset:224
	v_lshlrev_b32_e32 v225, 10, v226
	v_lshlrev_b32_e32 v0, 4, v224
	s_mov_b64 s[4:5], 0x20080
	v_add3_u32 v231, 0, v225, v0
	v_lshl_add_u64 v[0:1], v[44:45], 0, s[4:5]
	s_add_i32 s4, s3, 0x4000
	s_mov_b32 s5, m0
	s_mov_b32 m0, s4
	s_nop 0
	global_load_lds_dwordx4 v[0:1], off
	s_mov_b32 m0, s5
	s_waitcnt vmcnt(3) lgkmcnt(0)
	s_barrier
	ds_read_b128 v[0:3], v231
	ds_read_b128 v[16:19], v231 offset:512
	s_waitcnt vmcnt(3) lgkmcnt(1)
	v_mfma_f32_32x32x16_bf16 v[0:15], v[0:3], v[128:131], 0
	ds_read_b128 v[32:35], v231 offset:2048
	ds_read_b128 v[36:39], v231 offset:2560
	s_mov_b64 s[4:5], 0x30080
	s_mov_b32 s6, 1
	s_mov_b32 s36, 0
	s_movk_i32 s59, 0x2000
	s_andn2_b64 vcc, exec, s[64:65]
	s_waitcnt lgkmcnt(2)
	v_mfma_f32_32x32x16_bf16 v[16:31], v[16:19], v[128:131], 0
	s_waitcnt vmcnt(2) lgkmcnt(1)
	v_mfma_f32_32x32x16_bf16 v[0:15], v[32:35], v[132:135], v[0:15]
	ds_read_b128 v[32:35], v231 offset:4608
	ds_read_b128 v[40:43], v231 offset:4096
	s_waitcnt lgkmcnt(2)
	v_mfma_f32_32x32x16_bf16 v[16:31], v[36:39], v[132:135], v[16:31]
	v_lshlrev_b32_e32 v36, 1, v195
	v_and_b32_e32 v229, 32, v36
	v_lshlrev_b32_e32 v36, 4, v195
	v_and_b32_e32 v36, 0xc0, v36
	v_add_u32_e32 v37, 0, v229
	v_lshl_or_b32 v230, v226, 8, v36
	v_add3_u32 v232, v37, v228, v230
	s_waitcnt vmcnt(1) lgkmcnt(0)
	v_mfma_f32_32x32x16_bf16 v[0:15], v[40:43], v[136:139], v[0:15]
	ds_read_b128 v[36:39], v231 offset:6656
	ds_read_b128 v[40:43], v231 offset:6144
	v_mfma_f32_32x32x16_bf16 v[16:31], v[32:35], v[136:139], v[16:31]
	s_waitcnt vmcnt(0) lgkmcnt(0)
	v_mfma_f32_32x32x16_bf16 v[0:15], v[40:43], v[140:143], v[0:15]
	v_mfma_f32_32x32x16_bf16 v[16:31], v[36:39], v[140:143], v[16:31]
	s_nop 15
	s_nop 7
	s_waitcnt vmcnt(0) lgkmcnt(0)
	s_barrier
	s_nop 10
	v_exp_f32_e32 v80, v0
	v_exp_f32_e32 v81, v1
	v_lshl_add_u64 v[0:1], v[44:45], 0, s[4:5]
	s_mov_b32 s4, m0
	s_mov_b32 m0, s3
	s_nop 0
	global_load_lds_dwordx4 v[0:1], off
	s_mov_b32 m0, s4
	v_lshl_add_u64 v[0:1], v[46:47], 0, s[12:13]
	s_add_i32 s4, s3, 0xa000
	s_mov_b32 s5, m0
	s_mov_b32 m0, s4
	s_nop 0
	global_load_lds_dwordx4 v[0:1], off
	s_mov_b32 m0, s5
	v_lshl_add_u64 v[0:1], v[46:47], 0, s[70:71]
	s_add_i32 s4, s3, 0xc000
	s_mov_b32 s5, m0
	s_mov_b32 m0, s4
	s_nop 0
	global_load_lds_dwordx4 v[0:1], off
	s_mov_b32 m0, s5
	ds_read_b128 v[188:191], v231 offset:8192
	ds_read_b128 v[180:183], v231 offset:8704
	ds_read_b128 v[184:187], v231 offset:10240
	ds_read_b128 v[176:179], v231 offset:10752
	ds_read_b128 v[172:175], v231 offset:12288
	ds_read_b128 v[168:171], v231 offset:12800
	ds_read_b128 v[164:167], v231 offset:14336
	ds_read_b128 v[160:163], v231 offset:14848
	v_exp_f32_e32 v82, v2
	v_exp_f32_e32 v83, v3
	v_exp_f32_e32 v84, v4
	v_exp_f32_e32 v85, v5
	v_exp_f32_e32 v86, v6
	v_exp_f32_e32 v87, v7
	s_waitcnt vmcnt(3) lgkmcnt(0)
	s_barrier
	v_and_b32_e32 v0, 3, v195
	v_lshlrev_b32_e32 v204, 4, v0
	s_cbranch_vccnz .LBB0_442
	s_lshl_b32 s4, s2, 8
	s_and_b32 s4, s4, 0xc000
	v_lshl_add_u64 v[0:1], s[0:1], 1, v[204:205]
	v_lshl_or_b32 v2, v194, 10, s4
	v_mov_b32_e32 v3, v205
	v_lshl_add_u64 v[0:1], v[0:1], 0, v[2:3]
	v_mov_b32_e32 v233, 0
	v_lshl_add_u64 v[192:193], s[92:93], 0, v[0:1]
	s_mov_b32 s38, 0
	s_mov_b32 s39, 6
	s_mov_b64 s[4:5], 0
	v_mov_b32_e32 v48, 0
	v_mov_b32_e32 v49, v233
	v_mov_b32_e32 v50, v233
	v_mov_b32_e32 v51, v233
	v_mov_b32_e32 v52, v233
	v_mov_b32_e32 v53, v233
	v_mov_b32_e32 v54, v233
	v_mov_b32_e32 v55, v233
	v_mov_b32_e32 v56, v233
	v_mov_b32_e32 v57, v233
	v_mov_b32_e32 v58, v233
	v_mov_b32_e32 v59, v233
	v_mov_b32_e32 v60, v233
	v_mov_b32_e32 v61, v233
	v_mov_b32_e32 v62, v233
	v_mov_b32_e32 v63, v233
	v_mov_b32_e32 v32, 0
	v_mov_b32_e32 v33, v233
	v_mov_b32_e32 v34, v233
	v_mov_b32_e32 v35, v233
	v_mov_b32_e32 v36, v233
	v_mov_b32_e32 v37, v233
	v_mov_b32_e32 v38, v233
	v_mov_b32_e32 v39, v233
	v_mov_b32_e32 v40, v233
	v_mov_b32_e32 v41, v233
	v_mov_b32_e32 v42, v233
	v_mov_b32_e32 v43, v233
	v_mov_b32_e32 v44, v233
	v_mov_b32_e32 v45, v233
	v_mov_b32_e32 v46, v233
	v_mov_b32_e32 v47, v233
	v_mov_b32_e32 v16, 0
	v_mov_b32_e32 v17, v233
	v_mov_b32_e32 v18, v233
	v_mov_b32_e32 v19, v233
	v_mov_b32_e32 v20, v233
	v_mov_b32_e32 v21, v233
	v_mov_b32_e32 v22, v233
	v_mov_b32_e32 v23, v233
	v_mov_b32_e32 v24, v233
	v_mov_b32_e32 v25, v233
	v_mov_b32_e32 v26, v233
	v_mov_b32_e32 v27, v233
	v_mov_b32_e32 v28, v233
	v_mov_b32_e32 v29, v233
	v_mov_b32_e32 v30, v233
	v_mov_b32_e32 v31, v233
	v_mov_b32_e32 v0, 0
	v_mov_b32_e32 v1, v233
	v_mov_b32_e32 v2, v233
	v_mov_b32_e32 v3, v233
	v_mov_b32_e32 v4, v233
	v_mov_b32_e32 v5, v233
	v_mov_b32_e32 v6, v233
	v_mov_b32_e32 v7, v233
	v_mov_b32_e32 v8, v233
	v_mov_b32_e32 v9, v233
	v_mov_b32_e32 v10, v233
	v_mov_b32_e32 v11, v233
	v_mov_b32_e32 v12, v233
	v_mov_b32_e32 v13, v233
	v_mov_b32_e32 v14, v233
	v_mov_b32_e32 v15, v233
	v_mov_b32_e32 v64, 0
	v_mov_b32_e32 v65, v233
	v_mov_b32_e32 v66, v233
	v_mov_b32_e32 v67, v233
	v_mov_b32_e32 v68, v233
	v_mov_b32_e32 v69, v233
	v_mov_b32_e32 v70, v233
	v_mov_b32_e32 v71, v233
	v_mov_b32_e32 v72, v233
	v_mov_b32_e32 v73, v233
	v_mov_b32_e32 v74, v233
	v_mov_b32_e32 v75, v233
	v_mov_b32_e32 v76, v233
	v_mov_b32_e32 v77, v233
	v_mov_b32_e32 v78, v233
	v_mov_b32_e32 v79, v233
	v_mov_b32_e32 v88, v233
	v_mov_b32_e32 v89, v233
	v_mov_b32_e32 v90, v233
	v_mov_b32_e32 v91, v233
	v_mov_b32_e32 v92, v233
	v_mov_b32_e32 v93, v233
	v_mov_b32_e32 v94, v233
	v_mov_b32_e32 v95, v233
	v_readfirstlane_b32 s98, v192
	v_readfirstlane_b32 s99, v193
	s_nop 1
	v_subrev_u32_e32 v238, s98, v206
	v_subrev_u32_e32 v239, s98, v192
	s_add_u32 s98, s98, s4
	s_addc_u32 s99, s99, s5
.LBB0_439:
	s_mov_b32 s36, s66
	s_mov_b32 s6, s39
	s_mov_b32 s37, s59
	v_lshl_add_u32 v221, s38, 1, v232
	ds_read_b64_tr_b16 v[196:197], v221 offset:24576
	ds_read_b64_tr_b16 v[198:199], v221 offset:25088
	v_add_f32_e32 v96, v80, v81
	v_add_f32_e32 v96, v82, v96
	v_add_f32_e32 v96, v83, v96
	v_add_f32_e32 v96, v84, v96
	v_add_f32_e32 v96, v85, v96
	v_cvt_pk_bf16_f32 v144, v80, v81
	v_cvt_pk_bf16_f32 v145, v82, v83
	s_waitcnt lgkmcnt(9)
	v_mfma_f32_32x32x16_bf16 v[112:127], v[188:191], v[128:131], 0
	ds_read_b64_tr_b16 v[80:81], v221 offset:28672
	ds_read_b64_tr_b16 v[82:83], v221 offset:29184
	v_add_f32_e32 v96, v86, v96
	v_add_f32_e32 v96, v87, v96
	v_add_f32_e32 v96, v88, v96
	v_add_f32_e32 v148, v89, v96
	v_cvt_pk_bf16_f32 v146, v84, v85
	v_cvt_pk_bf16_f32 v147, v86, v87
	s_waitcnt lgkmcnt(10)
	v_mfma_f32_32x32x16_bf16 v[96:111], v[180:183], v[128:131], 0
	ds_read_b64_tr_b16 v[84:85], v221 offset:25600
	ds_read_b64_tr_b16 v[86:87], v221 offset:26112
	v_add_f32_e32 v148, v90, v148
	v_add_f32_e32 v148, v91, v148
	v_add_f32_e32 v148, v92, v148
	v_add_f32_e32 v152, v93, v148
	v_cvt_pk_bf16_f32 v148, v88, v89
	v_cvt_pk_bf16_f32 v149, v90, v91
	s_waitcnt lgkmcnt(11)
	v_mfma_f32_32x32x16_bf16 v[112:127], v[184:187], v[132:135], v[112:127]
	ds_read_b64_tr_b16 v[88:89], v221 offset:29696
	ds_read_b64_tr_b16 v[90:91], v221 offset:30208
	v_add_f32_e32 v150, v94, v152
	v_add_f32_e32 v150, v95, v150
	v_add_f32_e32 v150, v64, v150
	v_add_f32_e32 v152, v65, v150
	v_cvt_pk_bf16_f32 v150, v92, v93
	v_cvt_pk_bf16_f32 v151, v94, v95
	s_waitcnt lgkmcnt(12)
	v_mfma_f32_32x32x16_bf16 v[96:111], v[176:179], v[132:135], v[96:111]
	ds_read_b64_tr_b16 v[92:93], v221 offset:26624
	ds_read_b64_tr_b16 v[94:95], v221 offset:27136
	v_add_f32_e32 v152, v66, v152
	v_add_f32_e32 v152, v67, v152
	v_add_f32_e32 v152, v68, v152
	v_add_f32_e32 v156, v69, v152
	v_cvt_pk_bf16_f32 v152, v64, v65
	v_cvt_pk_bf16_f32 v153, v66, v67
	s_waitcnt lgkmcnt(13)
	v_mfma_f32_32x32x16_bf16 v[112:127], v[172:175], v[136:139], v[112:127]
	ds_read_b64_tr_b16 v[200:201], v221 offset:30720
	ds_read_b64_tr_b16 v[202:203], v221 offset:31232
	v_add_f32_e32 v64, v70, v156
	v_add_f32_e32 v64, v71, v64
	v_add_f32_e32 v64, v72, v64
	v_add_f32_e32 v64, v73, v64
	v_cvt_pk_bf16_f32 v154, v68, v69
	v_cvt_pk_bf16_f32 v155, v70, v71
	s_waitcnt lgkmcnt(14)
	v_mfma_f32_32x32x16_bf16 v[96:111], v[168:171], v[136:139], v[96:111]
	ds_read_b64_tr_b16 v[208:209], v221 offset:27648
	ds_read_b64_tr_b16 v[210:211], v221 offset:28160
	v_add_f32_e32 v64, v74, v64
	v_add_f32_e32 v64, v75, v64
	v_add_f32_e32 v64, v76, v64
	v_add_f32_e32 v64, v77, v64
	v_cvt_pk_bf16_f32 v156, v72, v73
	v_cvt_pk_bf16_f32 v157, v74, v75
	s_waitcnt lgkmcnt(14)
	v_mfma_f32_32x32x16_bf16 v[112:127], v[164:167], v[140:143], v[112:127]
	ds_read_b64_tr_b16 v[72:73], v221 offset:31744
	ds_read_b64_tr_b16 v[74:75], v221 offset:32256
	v_add_f32_e32 v64, v78, v64
	v_add_f32_e32 v64, v79, v64
	v_add_f32_e32 v64, 0, v64
	v_cvt_pk_bf16_f32 v158, v76, v77
	v_cvt_pk_bf16_f32 v159, v78, v79
	v_mfma_f32_32x32x16_bf16 v[96:111], v[160:163], v[140:143], v[96:111]
	s_add_i32 s38, s59, s3
	v_add_f32_e32 v188, v233, v64
	s_mov_b32 m0, s38
	s_add_u32 s100, s98, s72
	s_addc_u32 s101, s99, s73
	global_load_lds_dwordx4 v238, s[100:101]
	s_lshl_b32 s38, s66, 1
	s_add_i32 s38, s38, s35
	s_mov_b32 m0, s38
	s_add_u32 s100, s98, s74
	s_addc_u32 s101, s99, s75
	global_load_lds_dwordx4 v239, s[100:101]
	s_addk_i32 s38, 0x2000
	s_mov_b32 m0, s38
	s_add_u32 s100, s98, s76
	s_addc_u32 s101, s99, s77
	global_load_lds_dwordx4 v239, s[100:101]
	s_waitcnt lgkmcnt(14)
	v_mfma_f32_32x32x16_bf16 v[48:63], v[144:147], v[196:199], v[48:63]
	v_exp_f32_e32 v112, v112
	v_exp_f32_e32 v113, v113
	ds_read_b64_tr_b16 v[76:77], v221 offset:32768
	ds_read_b64_tr_b16 v[78:79], v221 offset:33280
	s_waitcnt lgkmcnt(14)
	v_mfma_f32_32x32x16_bf16 v[32:47], v[144:147], v[80:83], v[32:47]
	v_exp_f32_e32 v114, v114
	v_exp_f32_e32 v115, v115
	ds_read_b64_tr_b16 v[80:81], v221 offset:36864
	ds_read_b64_tr_b16 v[82:83], v221 offset:37376
	v_add_u32_e32 v160, s36, v231
	ds_read_b128 v[68:71], v160
	ds_read_b128 v[64:67], v160 offset:512
	s_waitcnt lgkmcnt(14)
	v_mfma_f32_32x32x16_bf16 v[48:63], v[148:151], v[84:87], v[48:63]
	v_exp_f32_e32 v116, v116
	v_exp_f32_e32 v117, v117
	ds_read_b64_tr_b16 v[84:85], v221 offset:33792
	ds_read_b64_tr_b16 v[86:87], v221 offset:34304
	ds_read_b128 v[180:183], v160 offset:2048
	ds_read_b128 v[176:179], v160 offset:2560
	v_mfma_f32_32x32x16_bf16 v[32:47], v[148:151], v[88:91], v[32:47]
	v_exp_f32_e32 v118, v118
	v_exp_f32_e32 v119, v119
	ds_read_b64_tr_b16 v[88:89], v221 offset:37888
	ds_read_b64_tr_b16 v[90:91], v221 offset:38400
	ds_read_b128 v[172:175], v160 offset:4096
	ds_read_b128 v[168:171], v160 offset:4608
	s_waitcnt lgkmcnt(14)
	v_mfma_f32_32x32x16_bf16 v[48:63], v[152:155], v[92:95], v[48:63]
	v_exp_f32_e32 v120, v120
	v_exp_f32_e32 v121, v121
	ds_read_b64_tr_b16 v[92:93], v221 offset:34816
	ds_read_b64_tr_b16 v[94:95], v221 offset:35328
	ds_read_b128 v[164:167], v160 offset:6144
	ds_read_b128 v[160:163], v160 offset:6656
	v_mfma_f32_32x32x16_bf16 v[32:47], v[152:155], v[200:203], v[32:47]
	v_exp_f32_e32 v122, v122
	v_exp_f32_e32 v123, v123
	ds_read_b64_tr_b16 v[196:197], v221 offset:38912
	ds_read_b64_tr_b16 v[198:199], v221 offset:39424
	v_mfma_f32_32x32x16_bf16 v[48:63], v[156:159], v[208:211], v[48:63]
	v_exp_f32_e32 v124, v124
	v_exp_f32_e32 v125, v125
	ds_read_b64_tr_b16 v[200:201], v221 offset:35840
	ds_read_b64_tr_b16 v[202:203], v221 offset:36352
	v_mfma_f32_32x32x16_bf16 v[32:47], v[156:159], v[72:75], v[32:47]
	v_exp_f32_e32 v126, v126
	v_exp_f32_e32 v127, v127
	ds_read_b64_tr_b16 v[72:73], v221 offset:39936
	ds_read_b64_tr_b16 v[74:75], v221 offset:40448
	s_waitcnt lgkmcnt(14)
	v_mfma_f32_32x32x16_bf16 v[16:31], v[144:147], v[76:79], v[16:31]
	v_exp_f32_e32 v96, v96
	v_exp_f32_e32 v97, v97
	v_mfma_f32_32x32x16_bf16 v[0:15], v[144:147], v[80:83], v[0:15]
	v_exp_f32_e32 v98, v98
	v_exp_f32_e32 v99, v99
	v_mfma_f32_32x32x16_bf16 v[16:31], v[148:151], v[84:87], v[16:31]
	v_exp_f32_e32 v100, v100
	v_exp_f32_e32 v101, v101
	s_waitcnt lgkmcnt(12)
	v_mfma_f32_32x32x16_bf16 v[0:15], v[148:151], v[88:91], v[0:15]
	v_exp_f32_e32 v102, v102
	v_exp_f32_e32 v103, v103
	s_waitcnt lgkmcnt(8)
	v_mfma_f32_32x32x16_bf16 v[16:31], v[152:155], v[92:95], v[16:31]
	v_exp_f32_e32 v104, v104
	v_exp_f32_e32 v105, v105
	s_waitcnt lgkmcnt(4)
	v_mfma_f32_32x32x16_bf16 v[0:15], v[152:155], v[196:199], v[0:15]
	v_exp_f32_e32 v106, v106
	v_exp_f32_e32 v107, v107
	s_waitcnt lgkmcnt(2)
	v_mfma_f32_32x32x16_bf16 v[16:31], v[156:159], v[200:203], v[16:31]
	v_exp_f32_e32 v108, v108
	v_exp_f32_e32 v109, v109
	s_waitcnt lgkmcnt(0)
	v_mfma_f32_32x32x16_bf16 v[0:15], v[156:159], v[72:75], v[0:15]
	v_exp_f32_e32 v110, v110
	v_exp_f32_e32 v111, v111
	s_waitcnt vmcnt(3) lgkmcnt(0)
	s_barrier
	s_add_i32 s38, s66, 0x2000
	s_cmpk_lg_i32 s66, 0x4000
	s_cselect_b32 s59, s38, 0
	v_lshl_add_u32 v200, s37, 1, v232
	ds_read_b64_tr_b16 v[196:197], v200 offset:24576
	ds_read_b64_tr_b16 v[198:199], v200 offset:25088
	v_mfma_f32_32x32x16_bf16 v[80:95], v[68:71], v[128:131], 0
	v_add_f32_e32 v72, v112, v113
	v_add_f32_e32 v72, v114, v72
	v_add_f32_e32 v72, v115, v72
	v_add_f32_e32 v72, v116, v72
	v_add_f32_e32 v72, v117, v72
	v_cvt_pk_bf16_f32 v144, v112, v113
	v_cvt_pk_bf16_f32 v145, v114, v115
	ds_read_b64_tr_b16 v[112:113], v200 offset:28672
	ds_read_b64_tr_b16 v[114:115], v200 offset:29184
	v_add_f32_e32 v68, v118, v72
	v_add_f32_e32 v68, v119, v68
	v_add_f32_e32 v68, v120, v68
	v_add_f32_e32 v148, v121, v68
	v_mfma_f32_32x32x16_bf16 v[64:79], v[64:67], v[128:131], 0
	v_cvt_pk_bf16_f32 v146, v116, v117
	v_cvt_pk_bf16_f32 v147, v118, v119
	ds_read_b64_tr_b16 v[116:117], v200 offset:25600
	ds_read_b64_tr_b16 v[118:119], v200 offset:26112
	v_mfma_f32_32x32x16_bf16 v[80:95], v[180:183], v[132:135], v[80:95]
	v_add_f32_e32 v148, v122, v148
	v_add_f32_e32 v148, v123, v148
	v_add_f32_e32 v148, v124, v148
	v_add_f32_e32 v152, v125, v148
	v_cvt_pk_bf16_f32 v148, v120, v121
	v_cvt_pk_bf16_f32 v149, v122, v123
	ds_read_b64_tr_b16 v[120:121], v200 offset:29696
	ds_read_b64_tr_b16 v[122:123], v200 offset:30208
	v_mfma_f32_32x32x16_bf16 v[64:79], v[176:179], v[132:135], v[64:79]
	v_add_f32_e32 v150, v126, v152
	v_add_f32_e32 v150, v127, v150
	v_add_f32_e32 v150, v96, v150
	v_add_f32_e32 v152, v97, v150
	v_cvt_pk_bf16_f32 v150, v124, v125
	v_cvt_pk_bf16_f32 v151, v126, v127
	ds_read_b64_tr_b16 v[124:125], v200 offset:26624
	ds_read_b64_tr_b16 v[126:127], v200 offset:27136
	v_mfma_f32_32x32x16_bf16 v[80:95], v[172:175], v[136:139], v[80:95]
	v_add_f32_e32 v152, v98, v152
	v_add_f32_e32 v152, v99, v152
	v_add_f32_e32 v152, v100, v152
	v_add_f32_e32 v156, v101, v152
	v_cvt_pk_bf16_f32 v152, v96, v97
	v_cvt_pk_bf16_f32 v153, v98, v99
	ds_read_b64_tr_b16 v[96:97], v200 offset:30720
	ds_read_b64_tr_b16 v[98:99], v200 offset:31232
	v_mfma_f32_32x32x16_bf16 v[64:79], v[168:171], v[136:139], v[64:79]
	v_add_f32_e32 v154, v102, v156
	v_add_f32_e32 v154, v103, v154
	v_add_f32_e32 v154, v104, v154
	v_add_f32_e32 v156, v105, v154
	v_cvt_pk_bf16_f32 v154, v100, v101
	v_cvt_pk_bf16_f32 v155, v102, v103
	ds_read_b64_tr_b16 v[100:101], v200 offset:27648
	ds_read_b64_tr_b16 v[102:103], v200 offset:28160
	v_mfma_f32_32x32x16_bf16 v[80:95], v[164:167], v[140:143], v[80:95]
	v_add_f32_e32 v156, v106, v156
	v_add_f32_e32 v156, v107, v156
	v_add_f32_e32 v156, v108, v156
	v_add_f32_e32 v164, v109, v156
	v_cvt_pk_bf16_f32 v156, v104, v105
	v_cvt_pk_bf16_f32 v157, v106, v107
	ds_read_b64_tr_b16 v[104:105], v200 offset:31744
	ds_read_b64_tr_b16 v[106:107], v200 offset:32256
	v_mfma_f32_32x32x16_bf16 v[64:79], v[160:163], v[140:143], v[64:79]
	v_add_f32_e32 v158, v110, v164
	v_add_f32_e32 v158, v111, v158
	v_add_f32_e32 v160, 0, v158
	v_cvt_pk_bf16_f32 v158, v108, v109
	v_cvt_pk_bf16_f32 v159, v110, v111
	s_add_i32 s37, s66, s3
	s_mov_b32 m0, s37
	s_add_u32 s100, s98, s78
	s_addc_u32 s101, s99, s79
	global_load_lds_dwordx4 v238, s[100:101]
	s_lshl_b32 s37, s59, 1
	s_add_i32 s37, s37, s35
	s_mov_b32 m0, s37
	s_add_u32 s100, s98, s80
	s_addc_u32 s101, s99, s81
	global_load_lds_dwordx4 v239, s[100:101]
	s_addk_i32 s37, 0x2000
	s_mov_b32 m0, s37
	s_add_u32 s100, s98, s82
	s_addc_u32 s101, s99, s83
	global_load_lds_dwordx4 v239, s[100:101]
	v_add_f32_e32 v233, v188, v160
	s_waitcnt lgkmcnt(14)
	v_mfma_f32_32x32x16_bf16 v[48:63], v[144:147], v[196:199], v[48:63]
	v_exp_f32_e32 v80, v80
	v_exp_f32_e32 v81, v81
	ds_read_b64_tr_b16 v[108:109], v200 offset:32768
	ds_read_b64_tr_b16 v[110:111], v200 offset:33280
	s_waitcnt lgkmcnt(14)
	v_mfma_f32_32x32x16_bf16 v[32:47], v[144:147], v[112:115], v[32:47]
	v_exp_f32_e32 v82, v82
	v_exp_f32_e32 v83, v83
	ds_read_b64_tr_b16 v[112:113], v200 offset:36864
	ds_read_b64_tr_b16 v[114:115], v200 offset:37376
	v_add_u32_e32 v160, s59, v231
	ds_read_b128 v[188:191], v160
	ds_read_b128 v[180:183], v160 offset:512
	s_waitcnt lgkmcnt(14)
	v_mfma_f32_32x32x16_bf16 v[48:63], v[148:151], v[116:119], v[48:63]
	v_exp_f32_e32 v84, v84
	v_exp_f32_e32 v85, v85
	ds_read_b64_tr_b16 v[116:117], v200 offset:33792
	ds_read_b64_tr_b16 v[118:119], v200 offset:34304
	ds_read_b128 v[184:187], v160 offset:2048
	ds_read_b128 v[176:179], v160 offset:2560
	v_mfma_f32_32x32x16_bf16 v[32:47], v[148:151], v[120:123], v[32:47]
	v_exp_f32_e32 v86, v86
	v_exp_f32_e32 v87, v87
	ds_read_b64_tr_b16 v[120:121], v200 offset:37888
	ds_read_b64_tr_b16 v[122:123], v200 offset:38400
	ds_read_b128 v[172:175], v160 offset:4096
	ds_read_b128 v[168:171], v160 offset:4608
	s_waitcnt lgkmcnt(14)
	v_mfma_f32_32x32x16_bf16 v[48:63], v[152:155], v[124:127], v[48:63]
	v_exp_f32_e32 v88, v88
	v_exp_f32_e32 v89, v89
	ds_read_b64_tr_b16 v[124:125], v200 offset:34816
	ds_read_b64_tr_b16 v[126:127], v200 offset:35328
	ds_read_b128 v[164:167], v160 offset:6144
	ds_read_b128 v[160:163], v160 offset:6656
	v_mfma_f32_32x32x16_bf16 v[32:47], v[152:155], v[96:99], v[32:47]
	v_exp_f32_e32 v90, v90
	v_exp_f32_e32 v91, v91
	ds_read_b64_tr_b16 v[96:97], v200 offset:38912
	ds_read_b64_tr_b16 v[98:99], v200 offset:39424
	v_mfma_f32_32x32x16_bf16 v[48:63], v[156:159], v[100:103], v[48:63]
	v_exp_f32_e32 v92, v92
	v_exp_f32_e32 v93, v93
	ds_read_b64_tr_b16 v[100:101], v200 offset:35840
	ds_read_b64_tr_b16 v[102:103], v200 offset:36352
	v_mfma_f32_32x32x16_bf16 v[32:47], v[156:159], v[104:107], v[32:47]
	v_exp_f32_e32 v94, v94
	v_exp_f32_e32 v95, v95
	ds_read_b64_tr_b16 v[104:105], v200 offset:39936
	ds_read_b64_tr_b16 v[106:107], v200 offset:40448
	s_waitcnt lgkmcnt(14)
	v_mfma_f32_32x32x16_bf16 v[16:31], v[144:147], v[108:111], v[16:31]
	v_exp_f32_e32 v64, v64
	v_exp_f32_e32 v65, v65
	v_mfma_f32_32x32x16_bf16 v[0:15], v[144:147], v[112:115], v[0:15]
	v_exp_f32_e32 v66, v66
	v_exp_f32_e32 v67, v67
	v_mfma_f32_32x32x16_bf16 v[16:31], v[148:151], v[116:119], v[16:31]
	v_exp_f32_e32 v68, v68
	v_exp_f32_e32 v69, v69
	s_waitcnt lgkmcnt(12)
	v_mfma_f32_32x32x16_bf16 v[0:15], v[148:151], v[120:123], v[0:15]
	v_exp_f32_e32 v70, v70
	v_exp_f32_e32 v71, v71
	s_waitcnt lgkmcnt(8)
	v_mfma_f32_32x32x16_bf16 v[16:31], v[152:155], v[124:127], v[16:31]
	v_exp_f32_e32 v72, v72
	v_exp_f32_e32 v73, v73
	s_waitcnt lgkmcnt(4)
	v_mfma_f32_32x32x16_bf16 v[0:15], v[152:155], v[96:99], v[0:15]
	v_exp_f32_e32 v74, v74
	v_exp_f32_e32 v75, v75
	s_waitcnt lgkmcnt(2)
	v_mfma_f32_32x32x16_bf16 v[16:31], v[156:159], v[100:103], v[16:31]
	v_exp_f32_e32 v76, v76
	v_exp_f32_e32 v77, v77
	s_waitcnt lgkmcnt(0)
	v_mfma_f32_32x32x16_bf16 v[0:15], v[156:159], v[104:107], v[0:15]
	v_exp_f32_e32 v78, v78
	v_exp_f32_e32 v79, v79
	s_add_i32 s37, s59, 0x2000
	s_cmpk_lg_i32 s59, 0x4000
	s_cselect_b32 s66, s37, 0
	s_add_i32 s39, s6, 2
	s_waitcnt vmcnt(3) lgkmcnt(0)
	s_barrier
	s_add_u32 s4, s4, 0x20000
	s_addc_u32 s5, s5, 0
	s_add_u32 s98, s98, 0x20000
	s_addc_u32 s99, s99, 0
	s_cmp_gt_u32 s39, s57
	s_mov_b32 s38, s36
	s_cbranch_scc0 .LBB0_439
	s_add_i32 s6, s6, -3
	s_branch .LBB0_443
